# hand-scheduled differential-attention 64-key step for off-band tiles
# speedup vs baseline: 1.0512x; 1.0076x over previous
.LBB0_1011:
	v_readlane_b32 s0, v254, 2
	s_add_i32 s27, s0, s29
	s_add_i32 s0, s27, -3
	s_cmp_gt_i32 s0, -1
	s_cselect_b64 s[4:5], -1, 0
	s_cmp_gt_i32 s31, s28
	s_cselect_b64 s[0:1], -1, 0
	s_and_b64 s[0:1], s[4:5], s[0:1]
	s_and_b64 vcc, exec, s[0:1]
	s_cbranch_vccnz .LBB0_1017
	s_add_i32 s0, s27, -3
	s_cmp_gt_i32 s0, -1
	s_cbranch_scc1 .Ldif_band0
	v_add_u32_e32 v64, v186, v185
	ds_read_b128 v[226:229], v188
	ds_read_b128 v[230:233], v188 offset:4608
	ds_read_b128 v[234:237], v188 offset:32
	ds_read_b128 v[238:241], v188 offset:4640
	s_waitcnt lgkmcnt(3)
	v_mfma_f32_32x32x16_bf16 v[66:81], v[226:229], v[122:125], 0
	ds_read_b128 v[226:229], v188 offset:64
	s_waitcnt lgkmcnt(3)
	v_mfma_f32_32x32x16_bf16 v[82:97], v[230:233], v[122:125], 0
	ds_read_b128 v[230:233], v188 offset:4672
	s_waitcnt lgkmcnt(3)
	v_mfma_f32_32x32x16_bf16 v[66:81], v[234:237], v[114:117], v[66:81]
	ds_read_b128 v[234:237], v188 offset:96
	s_waitcnt lgkmcnt(3)
	v_mfma_f32_32x32x16_bf16 v[82:97], v[238:241], v[114:117], v[82:97]
	ds_read_b128 v[238:241], v188 offset:4704
	s_waitcnt lgkmcnt(3)
	v_mfma_f32_32x32x16_bf16 v[130:145], v[226:229], v[118:121], 0
	ds_read_b128 v[242:245], v64 offset:18432
	s_nop 4
	v_exp_f32_e32 v66, v66
	v_exp_f32_e32 v67, v67
	v_exp_f32_e32 v68, v68
	v_exp_f32_e32 v69, v69
	v_mov_b32_e32 v189, v66
	v_mov_b32_e32 v190, v67
	v_mov_b32_e32 v191, v68
	v_mov_b32_e32 v192, v69
	v_cvt_pk_bf16_f32 v66, v66, v67
	v_cvt_pk_bf16_f32 v67, v68, v69
	v_exp_f32_e32 v70, v70
	v_exp_f32_e32 v71, v71
	v_exp_f32_e32 v72, v72
	v_exp_f32_e32 v73, v73
	v_add_f32_e32 v189, v189, v70
	v_add_f32_e32 v190, v190, v71
	v_add_f32_e32 v191, v191, v72
	v_add_f32_e32 v192, v192, v73
	v_cvt_pk_bf16_f32 v68, v70, v71
	v_cvt_pk_bf16_f32 v69, v72, v73
	s_waitcnt lgkmcnt(3)
	v_mfma_f32_32x32x16_bf16 v[146:161], v[230:233], v[118:121], 0
	ds_read_b128 v[246:249], v64 offset:23040
	v_exp_f32_e32 v74, v74
	v_exp_f32_e32 v75, v75
	v_exp_f32_e32 v76, v76
	v_exp_f32_e32 v77, v77
	v_add_f32_e32 v189, v189, v74
	v_add_f32_e32 v190, v190, v75
	v_add_f32_e32 v191, v191, v76
	v_add_f32_e32 v192, v192, v77
	v_cvt_pk_bf16_f32 v70, v74, v75
	v_cvt_pk_bf16_f32 v71, v76, v77
	v_exp_f32_e32 v78, v78
	v_exp_f32_e32 v79, v79
	v_exp_f32_e32 v80, v80
	v_exp_f32_e32 v81, v81
	v_add_f32_e32 v189, v189, v78
	v_add_f32_e32 v190, v190, v79
	v_add_f32_e32 v191, v191, v80
	v_add_f32_e32 v192, v192, v81
	v_cvt_pk_bf16_f32 v72, v78, v79
	v_cvt_pk_bf16_f32 v73, v80, v81
	s_waitcnt lgkmcnt(3)
	v_mfma_f32_32x32x16_bf16 v[130:145], v[234:237], v[126:129], v[130:145]
	ds_read_b128 v[164:167], v64 offset:18448
	v_exp_f32_e32 v82, v82
	v_exp_f32_e32 v83, v83
	v_exp_f32_e32 v84, v84
	v_exp_f32_e32 v85, v85
	v_add_f32_e32 v189, v189, v82
	v_add_f32_e32 v190, v190, v83
	v_add_f32_e32 v191, v191, v84
	v_add_f32_e32 v192, v192, v85
	v_cvt_pk_bf16_f32 v82, v82, v83
	v_cvt_pk_bf16_f32 v83, v84, v85
	v_exp_f32_e32 v86, v86
	v_exp_f32_e32 v87, v87
	v_exp_f32_e32 v88, v88
	v_exp_f32_e32 v89, v89
	v_add_f32_e32 v189, v189, v86
	v_add_f32_e32 v190, v190, v87
	v_add_f32_e32 v191, v191, v88
	v_add_f32_e32 v192, v192, v89
	v_cvt_pk_bf16_f32 v84, v86, v87
	v_cvt_pk_bf16_f32 v85, v88, v89
	s_waitcnt lgkmcnt(3)
	v_mfma_f32_32x32x16_bf16 v[146:161], v[238:241], v[126:129], v[146:161]
	ds_read_b128 v[198:201], v64 offset:23056
	v_exp_f32_e32 v90, v90
	v_exp_f32_e32 v91, v91
	v_exp_f32_e32 v92, v92
	v_exp_f32_e32 v93, v93
	v_add_f32_e32 v189, v189, v90
	v_add_f32_e32 v190, v190, v91
	v_add_f32_e32 v191, v191, v92
	v_add_f32_e32 v192, v192, v93
	v_cvt_pk_bf16_f32 v86, v90, v91
	v_cvt_pk_bf16_f32 v87, v92, v93
	v_exp_f32_e32 v94, v94
	v_exp_f32_e32 v95, v95
	v_exp_f32_e32 v96, v96
	v_exp_f32_e32 v97, v97
	v_add_f32_e32 v189, v189, v94
	v_add_f32_e32 v190, v190, v95
	v_add_f32_e32 v191, v191, v96
	v_add_f32_e32 v192, v192, v97
	v_cvt_pk_bf16_f32 v88, v94, v95
	v_cvt_pk_bf16_f32 v89, v96, v97
	v_add_f32_e32 v189, v189, v190
	v_add_f32_e32 v191, v191, v192
	v_add_f32_e32 v189, v189, v191
	v_add_f32_e32 v171, v171, v189
	s_waitcnt lgkmcnt(3)
	v_mfma_f32_32x32x16_bf16 v[16:31], v[242:245], v[66:69], v[16:31]
	ds_read_b128 v[242:245], v64 offset:18496
	v_exp_f32_e32 v130, v130
	v_exp_f32_e32 v131, v131
	v_exp_f32_e32 v132, v132
	v_exp_f32_e32 v133, v133
	v_mov_b32_e32 v189, v130
	v_mov_b32_e32 v190, v131
	v_mov_b32_e32 v191, v132
	v_mov_b32_e32 v192, v133
	v_cvt_pk_bf16_f32 v130, v130, v131
	v_cvt_pk_bf16_f32 v131, v132, v133
	s_waitcnt lgkmcnt(3)
	v_mfma_f32_32x32x16_bf16 v[0:15], v[246:249], v[66:69], v[0:15]
	ds_read_b128 v[246:249], v64 offset:23104
	v_exp_f32_e32 v134, v134
	v_exp_f32_e32 v135, v135
	v_exp_f32_e32 v136, v136
	v_exp_f32_e32 v137, v137
	v_add_f32_e32 v189, v189, v134
	v_add_f32_e32 v190, v190, v135
	v_add_f32_e32 v191, v191, v136
	v_add_f32_e32 v192, v192, v137
	v_cvt_pk_bf16_f32 v132, v134, v135
	v_cvt_pk_bf16_f32 v133, v136, v137
	s_waitcnt lgkmcnt(3)
	v_mfma_f32_32x32x16_bf16 v[16:31], v[164:167], v[70:73], v[16:31]
	ds_read_b128 v[164:167], v64 offset:18512
	v_exp_f32_e32 v138, v138
	v_exp_f32_e32 v139, v139
	v_exp_f32_e32 v140, v140
	v_exp_f32_e32 v141, v141
	v_add_f32_e32 v189, v189, v138
	v_add_f32_e32 v190, v190, v139
	v_add_f32_e32 v191, v191, v140
	v_add_f32_e32 v192, v192, v141
	v_cvt_pk_bf16_f32 v134, v138, v139
	v_cvt_pk_bf16_f32 v135, v140, v141
	s_waitcnt lgkmcnt(3)
	v_mfma_f32_32x32x16_bf16 v[0:15], v[198:201], v[70:73], v[0:15]
	ds_read_b128 v[198:201], v64 offset:23120
	v_exp_f32_e32 v142, v142
	v_exp_f32_e32 v143, v143
	v_exp_f32_e32 v144, v144
	v_exp_f32_e32 v145, v145
	v_add_f32_e32 v189, v189, v142
	v_add_f32_e32 v190, v190, v143
	v_add_f32_e32 v191, v191, v144
	v_add_f32_e32 v192, v192, v145
	v_cvt_pk_bf16_f32 v136, v142, v143
	v_cvt_pk_bf16_f32 v137, v144, v145
	s_waitcnt lgkmcnt(3)
	v_mfma_f32_32x32x16_bf16 v[16:31], v[242:245], v[82:85], v[16:31]
	v_exp_f32_e32 v146, v146
	v_exp_f32_e32 v147, v147
	v_exp_f32_e32 v148, v148
	v_exp_f32_e32 v149, v149
	v_add_f32_e32 v189, v189, v146
	v_add_f32_e32 v190, v190, v147
	v_add_f32_e32 v191, v191, v148
	v_add_f32_e32 v192, v192, v149
	v_cvt_pk_bf16_f32 v146, v146, v147
	v_cvt_pk_bf16_f32 v147, v148, v149
	s_waitcnt lgkmcnt(2)
	v_mfma_f32_32x32x16_bf16 v[0:15], v[246:249], v[82:85], v[0:15]
	v_exp_f32_e32 v150, v150
	v_exp_f32_e32 v151, v151
	v_exp_f32_e32 v152, v152
	v_exp_f32_e32 v153, v153
	v_add_f32_e32 v189, v189, v150
	v_add_f32_e32 v190, v190, v151
	v_add_f32_e32 v191, v191, v152
	v_add_f32_e32 v192, v192, v153
	v_cvt_pk_bf16_f32 v148, v150, v151
	v_cvt_pk_bf16_f32 v149, v152, v153
	s_waitcnt lgkmcnt(1)
	v_mfma_f32_32x32x16_bf16 v[16:31], v[164:167], v[86:89], v[16:31]
	v_exp_f32_e32 v154, v154
	v_exp_f32_e32 v155, v155
	v_exp_f32_e32 v156, v156
	v_exp_f32_e32 v157, v157
	v_add_f32_e32 v189, v189, v154
	v_add_f32_e32 v190, v190, v155
	v_add_f32_e32 v191, v191, v156
	v_add_f32_e32 v192, v192, v157
	v_cvt_pk_bf16_f32 v150, v154, v155
	v_cvt_pk_bf16_f32 v151, v156, v157
	s_waitcnt lgkmcnt(0)
	v_mfma_f32_32x32x16_bf16 v[0:15], v[198:201], v[86:89], v[0:15]
	v_exp_f32_e32 v158, v158
	v_exp_f32_e32 v159, v159
	v_exp_f32_e32 v160, v160
	v_exp_f32_e32 v161, v161
	v_add_f32_e32 v189, v189, v158
	v_add_f32_e32 v190, v190, v159
	v_add_f32_e32 v191, v191, v160
	v_add_f32_e32 v192, v192, v161
	v_cvt_pk_bf16_f32 v152, v158, v159
	v_cvt_pk_bf16_f32 v153, v160, v161
	v_add_f32_e32 v189, v189, v190
	v_add_f32_e32 v191, v191, v192
	v_add_f32_e32 v189, v189, v191
	v_add_f32_e32 v169, v169, v189
	ds_read_b128 v[242:245], v64 offset:18432
	ds_read_b128 v[246:249], v64 offset:23040
	ds_read_b128 v[164:167], v64 offset:18448
	ds_read_b128 v[198:201], v64 offset:23056
	s_waitcnt lgkmcnt(3)
	v_mfma_f32_32x32x16_bf16 v[48:63], v[242:245], v[130:133], v[48:63]
	ds_read_b128 v[242:245], v64 offset:18496
	s_waitcnt lgkmcnt(3)
	v_mfma_f32_32x32x16_bf16 v[32:47], v[246:249], v[130:133], v[32:47]
	ds_read_b128 v[246:249], v64 offset:23104
	s_waitcnt lgkmcnt(3)
	v_mfma_f32_32x32x16_bf16 v[48:63], v[164:167], v[134:137], v[48:63]
	ds_read_b128 v[164:167], v64 offset:18512
	s_waitcnt lgkmcnt(3)
	v_mfma_f32_32x32x16_bf16 v[32:47], v[198:201], v[134:137], v[32:47]
	ds_read_b128 v[198:201], v64 offset:23120
	s_waitcnt lgkmcnt(3)
	v_mfma_f32_32x32x16_bf16 v[48:63], v[242:245], v[146:149], v[48:63]
	s_waitcnt lgkmcnt(2)
	v_mfma_f32_32x32x16_bf16 v[32:47], v[246:249], v[146:149], v[32:47]
	s_waitcnt lgkmcnt(1)
	v_mfma_f32_32x32x16_bf16 v[48:63], v[164:167], v[150:153], v[48:63]
	s_waitcnt lgkmcnt(0)
	v_mfma_f32_32x32x16_bf16 v[32:47], v[198:201], v[150:153], v[32:47]
	s_branch .LBB0_1017
.Ldif_band0:
	ds_read_b128 v[66:69], v188 offset:4608
	ds_read_b128 v[70:73], v188
	ds_read_b128 v[130:133], v188 offset:32
	ds_read_b128 v[134:137], v188 offset:4640
	v_cndmask_b32_e64 v64, 0, 1, s[4:5]
	v_cmp_ne_u32_e64 s[0:1], 1, v64
	s_waitcnt lgkmcnt(0)
	v_mfma_f32_32x32x16_bf16 v[82:97], v[70:73], v[122:125], 0
	s_andn2_b64 vcc, exec, s[4:5]
	v_cmp_gt_i32_e64 s[52:53], 0, v187
	v_cmp_gt_i32_e64 s[36:37], 32, v187
	v_cmp_gt_i32_e64 s[62:63], 1, v187
	v_cmp_gt_i32_e64 s[38:39], 33, v187
	v_cmp_gt_i32_e64 s[66:67], 2, v187
	v_cmp_gt_i32_e64 s[42:43], 34, v187
	v_mfma_f32_32x32x16_bf16 v[66:81], v[66:69], v[122:125], 0
	v_cmp_gt_i32_e64 s[72:73], 3, v187
	v_cmp_gt_i32_e64 s[44:45], 35, v187
	v_cmp_gt_i32_e64 s[76:77], 8, v187
	v_cmp_gt_i32_e64 s[46:47], 40, v187
	v_cmp_gt_i32_e64 s[80:81], 9, v187
	v_cmp_gt_i32_e64 s[48:49], 41, v187
	v_cmp_gt_i32_e64 s[82:83], 10, v187
	v_mfma_f32_32x32x16_bf16 v[82:97], v[130:133], v[114:117], v[82:97]
	v_cmp_gt_i32_e64 s[50:51], 42, v187
	v_cmp_gt_i32_e64 s[84:85], 11, v187
	v_cmp_gt_i32_e64 s[54:55], 43, v187
	v_cmp_gt_i32_e64 s[86:87], 16, v187
	v_cmp_gt_i32_e64 s[56:57], 48, v187
	v_cmp_gt_i32_e64 s[90:91], 17, v187
	v_cmp_gt_i32_e64 s[60:61], 49, v187
	v_mfma_f32_32x32x16_bf16 v[66:81], v[134:137], v[114:117], v[66:81]
	v_cmp_gt_i32_e64 s[92:93], 18, v187
	v_cmp_gt_i32_e64 s[64:65], 50, v187
	v_cmp_gt_i32_e64 s[94:95], 19, v187
	v_cmp_gt_i32_e64 s[68:69], 51, v187
	v_cmp_gt_i32_e64 s[96:97], 24, v187
	v_cmp_gt_i32_e64 s[70:71], 56, v187
	v_cmp_gt_i32_e64 s[6:7], 25, v187
	v_cmp_gt_i32_e64 s[74:75], 57, v187
	v_cmp_gt_i32_e64 s[4:5], 26, v187
	v_cmp_gt_i32_e64 s[78:79], 58, v187
	v_cmp_gt_i32_e64 s[88:89], 27, v187
	v_cmp_gt_i32_e64 s[58:59], 59, v187
	s_cbranch_vccnz .LBB0_1014
	s_and_b64 vcc, s[88:89], s[4:5]
	v_cndmask_b32_e32 v96, v96, v225, vcc
	s_and_b64 vcc, vcc, s[6:7]
	v_cndmask_b32_e32 v95, v95, v225, vcc
	s_and_b64 vcc, vcc, s[96:97]
	v_cndmask_b32_e32 v94, v94, v225, vcc
	s_and_b64 vcc, vcc, s[94:95]
	v_cndmask_b32_e32 v93, v93, v225, vcc
	s_and_b64 vcc, vcc, s[92:93]
	v_cndmask_b32_e32 v92, v92, v225, vcc
	s_and_b64 vcc, vcc, s[90:91]
	v_cndmask_b32_e32 v91, v91, v225, vcc
	s_and_b64 vcc, vcc, s[86:87]
	v_cndmask_b32_e32 v90, v90, v225, vcc
	s_and_b64 vcc, vcc, s[84:85]
	v_cndmask_b32_e32 v89, v89, v225, vcc
	s_and_b64 vcc, vcc, s[82:83]
	v_cndmask_b32_e32 v88, v88, v225, vcc
	s_and_b64 vcc, vcc, s[80:81]
	v_cndmask_b32_e32 v87, v87, v225, vcc
	s_and_b64 vcc, vcc, s[76:77]
	v_cndmask_b32_e32 v86, v86, v225, vcc
	s_and_b64 vcc, vcc, s[72:73]
	v_cndmask_b32_e32 v85, v85, v225, vcc
	s_and_b64 vcc, vcc, s[66:67]
	v_cndmask_b32_e32 v84, v84, v225, vcc
	s_and_b64 vcc, vcc, s[62:63]
	v_cndmask_b32_e32 v83, v83, v225, vcc
	s_and_b64 vcc, vcc, s[52:53]
	v_cndmask_b32_e32 v82, v82, v225, vcc
	s_and_b64 vcc, s[58:59], s[78:79]
	v_cndmask_b32_e32 v80, v80, v225, vcc
	s_and_b64 vcc, vcc, s[74:75]
	v_cndmask_b32_e32 v79, v79, v225, vcc
	s_and_b64 vcc, vcc, s[70:71]
	v_cndmask_b32_e32 v78, v78, v225, vcc
	s_and_b64 vcc, vcc, s[68:69]
	v_cndmask_b32_e32 v77, v77, v225, vcc
	s_and_b64 vcc, vcc, s[64:65]
	v_cndmask_b32_e32 v76, v76, v225, vcc
	s_and_b64 vcc, vcc, s[60:61]
	v_cndmask_b32_e32 v75, v75, v225, vcc
	s_and_b64 vcc, vcc, s[56:57]
	v_cndmask_b32_e32 v74, v74, v225, vcc
	s_and_b64 vcc, vcc, s[54:55]
	v_cndmask_b32_e32 v73, v73, v225, vcc
	s_and_b64 vcc, vcc, s[50:51]
	v_cndmask_b32_e32 v72, v72, v225, vcc
	s_and_b64 vcc, vcc, s[48:49]
	v_cndmask_b32_e32 v71, v71, v225, vcc
	s_and_b64 vcc, vcc, s[46:47]
	v_cndmask_b32_e32 v70, v70, v225, vcc
	s_and_b64 vcc, vcc, s[44:45]
	v_cndmask_b32_e32 v69, v69, v225, vcc
	s_and_b64 vcc, vcc, s[42:43]
	v_cndmask_b32_e32 v68, v68, v225, vcc
	s_and_b64 vcc, vcc, s[38:39]
	v_cndmask_b32_e32 v67, v67, v225, vcc
	s_and_b64 vcc, vcc, s[36:37]
	v_cndmask_b32_e64 v97, v97, v225, s[88:89]
	v_cndmask_b32_e32 v66, v66, v225, vcc
	v_cndmask_b32_e64 v81, v81, v225, s[58:59]

.LBB0_1021:
	s_add_i32 s27, s27, -2
	s_cmp_gt_i32 s27, -1
	s_cselect_b64 s[4:5], -1, 0
	s_add_i32 s0, s31, 64
	s_cmp_gt_i32 s0, s28
	s_cselect_b64 s[0:1], -1, 0
	s_and_b64 s[0:1], s[4:5], s[0:1]
	s_and_b64 vcc, exec, s[0:1]
	s_cbranch_vccnz .LBB0_1027
	s_cmp_gt_i32 s27, -1
	s_cbranch_scc1 .Ldif_band1
	v_add_u32_e32 v64, v186, v185
	ds_read_b128 v[226:229], v188 offset:9216
	ds_read_b128 v[230:233], v188 offset:13824
	ds_read_b128 v[234:237], v188 offset:9248
	ds_read_b128 v[238:241], v188 offset:13856
	s_waitcnt lgkmcnt(3)
	v_mfma_f32_32x32x16_bf16 v[66:81], v[226:229], v[122:125], 0
	ds_read_b128 v[226:229], v188 offset:9280
	s_waitcnt lgkmcnt(3)
	v_mfma_f32_32x32x16_bf16 v[82:97], v[230:233], v[122:125], 0
	ds_read_b128 v[230:233], v188 offset:13888
	s_waitcnt lgkmcnt(3)
	v_mfma_f32_32x32x16_bf16 v[66:81], v[234:237], v[114:117], v[66:81]
	ds_read_b128 v[234:237], v188 offset:9312
	s_waitcnt lgkmcnt(3)
	v_mfma_f32_32x32x16_bf16 v[82:97], v[238:241], v[114:117], v[82:97]
	ds_read_b128 v[238:241], v188 offset:13920
	s_waitcnt lgkmcnt(3)
	v_mfma_f32_32x32x16_bf16 v[130:145], v[226:229], v[118:121], 0
	ds_read_b128 v[242:245], v64 offset:27648
	s_nop 4
	v_exp_f32_e32 v66, v66
	v_exp_f32_e32 v67, v67
	v_exp_f32_e32 v68, v68
	v_exp_f32_e32 v69, v69
	v_mov_b32_e32 v189, v66
	v_mov_b32_e32 v190, v67
	v_mov_b32_e32 v191, v68
	v_mov_b32_e32 v192, v69
	v_cvt_pk_bf16_f32 v66, v66, v67
	v_cvt_pk_bf16_f32 v67, v68, v69
	v_exp_f32_e32 v70, v70
	v_exp_f32_e32 v71, v71
	v_exp_f32_e32 v72, v72
	v_exp_f32_e32 v73, v73
	v_add_f32_e32 v189, v189, v70
	v_add_f32_e32 v190, v190, v71
	v_add_f32_e32 v191, v191, v72
	v_add_f32_e32 v192, v192, v73
	v_cvt_pk_bf16_f32 v68, v70, v71
	v_cvt_pk_bf16_f32 v69, v72, v73
	s_waitcnt lgkmcnt(3)
	v_mfma_f32_32x32x16_bf16 v[146:161], v[230:233], v[118:121], 0
	ds_read_b128 v[246:249], v64 offset:32256
	v_exp_f32_e32 v74, v74
	v_exp_f32_e32 v75, v75
	v_exp_f32_e32 v76, v76
	v_exp_f32_e32 v77, v77
	v_add_f32_e32 v189, v189, v74
	v_add_f32_e32 v190, v190, v75
	v_add_f32_e32 v191, v191, v76
	v_add_f32_e32 v192, v192, v77
	v_cvt_pk_bf16_f32 v70, v74, v75
	v_cvt_pk_bf16_f32 v71, v76, v77
	v_exp_f32_e32 v78, v78
	v_exp_f32_e32 v79, v79
	v_exp_f32_e32 v80, v80
	v_exp_f32_e32 v81, v81
	v_add_f32_e32 v189, v189, v78
	v_add_f32_e32 v190, v190, v79
	v_add_f32_e32 v191, v191, v80
	v_add_f32_e32 v192, v192, v81
	v_cvt_pk_bf16_f32 v72, v78, v79
	v_cvt_pk_bf16_f32 v73, v80, v81
	s_waitcnt lgkmcnt(3)
	v_mfma_f32_32x32x16_bf16 v[130:145], v[234:237], v[126:129], v[130:145]
	ds_read_b128 v[164:167], v64 offset:27664
	v_exp_f32_e32 v82, v82
	v_exp_f32_e32 v83, v83
	v_exp_f32_e32 v84, v84
	v_exp_f32_e32 v85, v85
	v_add_f32_e32 v189, v189, v82
	v_add_f32_e32 v190, v190, v83
	v_add_f32_e32 v191, v191, v84
	v_add_f32_e32 v192, v192, v85
	v_cvt_pk_bf16_f32 v82, v82, v83
	v_cvt_pk_bf16_f32 v83, v84, v85
	v_exp_f32_e32 v86, v86
	v_exp_f32_e32 v87, v87
	v_exp_f32_e32 v88, v88
	v_exp_f32_e32 v89, v89
	v_add_f32_e32 v189, v189, v86
	v_add_f32_e32 v190, v190, v87
	v_add_f32_e32 v191, v191, v88
	v_add_f32_e32 v192, v192, v89
	v_cvt_pk_bf16_f32 v84, v86, v87
	v_cvt_pk_bf16_f32 v85, v88, v89
	s_waitcnt lgkmcnt(3)
	v_mfma_f32_32x32x16_bf16 v[146:161], v[238:241], v[126:129], v[146:161]
	ds_read_b128 v[198:201], v64 offset:32272
	v_exp_f32_e32 v90, v90
	v_exp_f32_e32 v91, v91
	v_exp_f32_e32 v92, v92
	v_exp_f32_e32 v93, v93
	v_add_f32_e32 v189, v189, v90
	v_add_f32_e32 v190, v190, v91
	v_add_f32_e32 v191, v191, v92
	v_add_f32_e32 v192, v192, v93
	v_cvt_pk_bf16_f32 v86, v90, v91
	v_cvt_pk_bf16_f32 v87, v92, v93
	v_exp_f32_e32 v94, v94
	v_exp_f32_e32 v95, v95
	v_exp_f32_e32 v96, v96
	v_exp_f32_e32 v97, v97
	v_add_f32_e32 v189, v189, v94
	v_add_f32_e32 v190, v190, v95
	v_add_f32_e32 v191, v191, v96
	v_add_f32_e32 v192, v192, v97
	v_cvt_pk_bf16_f32 v88, v94, v95
	v_cvt_pk_bf16_f32 v89, v96, v97
	v_add_f32_e32 v189, v189, v190
	v_add_f32_e32 v191, v191, v192
	v_add_f32_e32 v189, v189, v191
	v_add_f32_e32 v171, v171, v189
	s_waitcnt lgkmcnt(3)
	v_mfma_f32_32x32x16_bf16 v[16:31], v[242:245], v[66:69], v[16:31]
	ds_read_b128 v[242:245], v64 offset:27712
	v_exp_f32_e32 v130, v130
	v_exp_f32_e32 v131, v131
	v_exp_f32_e32 v132, v132
	v_exp_f32_e32 v133, v133
	v_mov_b32_e32 v189, v130
	v_mov_b32_e32 v190, v131
	v_mov_b32_e32 v191, v132
	v_mov_b32_e32 v192, v133
	v_cvt_pk_bf16_f32 v130, v130, v131
	v_cvt_pk_bf16_f32 v131, v132, v133
	s_waitcnt lgkmcnt(3)
	v_mfma_f32_32x32x16_bf16 v[0:15], v[246:249], v[66:69], v[0:15]
	ds_read_b128 v[246:249], v64 offset:32320
	v_exp_f32_e32 v134, v134
	v_exp_f32_e32 v135, v135
	v_exp_f32_e32 v136, v136
	v_exp_f32_e32 v137, v137
	v_add_f32_e32 v189, v189, v134
	v_add_f32_e32 v190, v190, v135
	v_add_f32_e32 v191, v191, v136
	v_add_f32_e32 v192, v192, v137
	v_cvt_pk_bf16_f32 v132, v134, v135
	v_cvt_pk_bf16_f32 v133, v136, v137
	s_waitcnt lgkmcnt(3)
	v_mfma_f32_32x32x16_bf16 v[16:31], v[164:167], v[70:73], v[16:31]
	ds_read_b128 v[164:167], v64 offset:27728
	v_exp_f32_e32 v138, v138
	v_exp_f32_e32 v139, v139
	v_exp_f32_e32 v140, v140
	v_exp_f32_e32 v141, v141
	v_add_f32_e32 v189, v189, v138
	v_add_f32_e32 v190, v190, v139
	v_add_f32_e32 v191, v191, v140
	v_add_f32_e32 v192, v192, v141
	v_cvt_pk_bf16_f32 v134, v138, v139
	v_cvt_pk_bf16_f32 v135, v140, v141
	s_waitcnt lgkmcnt(3)
	v_mfma_f32_32x32x16_bf16 v[0:15], v[198:201], v[70:73], v[0:15]
	ds_read_b128 v[198:201], v64 offset:32336
	v_exp_f32_e32 v142, v142
	v_exp_f32_e32 v143, v143
	v_exp_f32_e32 v144, v144
	v_exp_f32_e32 v145, v145
	v_add_f32_e32 v189, v189, v142
	v_add_f32_e32 v190, v190, v143
	v_add_f32_e32 v191, v191, v144
	v_add_f32_e32 v192, v192, v145
	v_cvt_pk_bf16_f32 v136, v142, v143
	v_cvt_pk_bf16_f32 v137, v144, v145
	s_waitcnt lgkmcnt(3)
	v_mfma_f32_32x32x16_bf16 v[16:31], v[242:245], v[82:85], v[16:31]
	v_exp_f32_e32 v146, v146
	v_exp_f32_e32 v147, v147
	v_exp_f32_e32 v148, v148
	v_exp_f32_e32 v149, v149
	v_add_f32_e32 v189, v189, v146
	v_add_f32_e32 v190, v190, v147
	v_add_f32_e32 v191, v191, v148
	v_add_f32_e32 v192, v192, v149
	v_cvt_pk_bf16_f32 v146, v146, v147
	v_cvt_pk_bf16_f32 v147, v148, v149
	s_waitcnt lgkmcnt(2)
	v_mfma_f32_32x32x16_bf16 v[0:15], v[246:249], v[82:85], v[0:15]
	v_exp_f32_e32 v150, v150
	v_exp_f32_e32 v151, v151
	v_exp_f32_e32 v152, v152
	v_exp_f32_e32 v153, v153
	v_add_f32_e32 v189, v189, v150
	v_add_f32_e32 v190, v190, v151
	v_add_f32_e32 v191, v191, v152
	v_add_f32_e32 v192, v192, v153
	v_cvt_pk_bf16_f32 v148, v150, v151
	v_cvt_pk_bf16_f32 v149, v152, v153
	s_waitcnt lgkmcnt(1)
	v_mfma_f32_32x32x16_bf16 v[16:31], v[164:167], v[86:89], v[16:31]
	v_exp_f32_e32 v154, v154
	v_exp_f32_e32 v155, v155
	v_exp_f32_e32 v156, v156
	v_exp_f32_e32 v157, v157
	v_add_f32_e32 v189, v189, v154
	v_add_f32_e32 v190, v190, v155
	v_add_f32_e32 v191, v191, v156
	v_add_f32_e32 v192, v192, v157
	v_cvt_pk_bf16_f32 v150, v154, v155
	v_cvt_pk_bf16_f32 v151, v156, v157
	s_waitcnt lgkmcnt(0)
	v_mfma_f32_32x32x16_bf16 v[0:15], v[198:201], v[86:89], v[0:15]
	v_exp_f32_e32 v158, v158
	v_exp_f32_e32 v159, v159
	v_exp_f32_e32 v160, v160
	v_exp_f32_e32 v161, v161
	v_add_f32_e32 v189, v189, v158
	v_add_f32_e32 v190, v190, v159
	v_add_f32_e32 v191, v191, v160
	v_add_f32_e32 v192, v192, v161
	v_cvt_pk_bf16_f32 v152, v158, v159
	v_cvt_pk_bf16_f32 v153, v160, v161
	v_add_f32_e32 v189, v189, v190
	v_add_f32_e32 v191, v191, v192
	v_add_f32_e32 v189, v189, v191
	v_add_f32_e32 v169, v169, v189
	ds_read_b128 v[242:245], v64 offset:27648
	ds_read_b128 v[246:249], v64 offset:32256
	ds_read_b128 v[164:167], v64 offset:27664
	ds_read_b128 v[198:201], v64 offset:32272
	s_waitcnt lgkmcnt(3)
	v_mfma_f32_32x32x16_bf16 v[48:63], v[242:245], v[130:133], v[48:63]
	ds_read_b128 v[242:245], v64 offset:27712
	s_waitcnt lgkmcnt(3)
	v_mfma_f32_32x32x16_bf16 v[32:47], v[246:249], v[130:133], v[32:47]
	ds_read_b128 v[246:249], v64 offset:32320
	s_waitcnt lgkmcnt(3)
	v_mfma_f32_32x32x16_bf16 v[48:63], v[164:167], v[134:137], v[48:63]
	ds_read_b128 v[164:167], v64 offset:27728
	s_waitcnt lgkmcnt(3)
	v_mfma_f32_32x32x16_bf16 v[32:47], v[198:201], v[134:137], v[32:47]
	ds_read_b128 v[198:201], v64 offset:32336
	s_waitcnt lgkmcnt(3)
	v_mfma_f32_32x32x16_bf16 v[48:63], v[242:245], v[146:149], v[48:63]
	s_waitcnt lgkmcnt(2)
	v_mfma_f32_32x32x16_bf16 v[32:47], v[246:249], v[146:149], v[32:47]
	s_waitcnt lgkmcnt(1)
	v_mfma_f32_32x32x16_bf16 v[48:63], v[164:167], v[150:153], v[48:63]
	s_waitcnt lgkmcnt(0)
	v_mfma_f32_32x32x16_bf16 v[32:47], v[198:201], v[150:153], v[32:47]
	s_branch .LBB0_1027
.Ldif_band1:
	ds_read_b128 v[66:69], v188 offset:13824
	ds_read_b128 v[70:73], v188 offset:9216
	ds_read_b128 v[130:133], v188 offset:9248
	ds_read_b128 v[134:137], v188 offset:13856
	v_subrev_u32_e32 v64, 64, v187
	s_andn2_b64 vcc, exec, s[4:5]
	s_waitcnt lgkmcnt(0)
	v_mfma_f32_32x32x16_bf16 v[82:97], v[70:73], v[122:125], 0
	v_cmp_gt_i32_e64 s[58:59], 0, v64
	v_cmp_gt_i32_e64 s[36:37], 32, v64
	v_cmp_gt_i32_e64 s[62:63], 1, v64
	v_cmp_gt_i32_e64 s[38:39], 33, v64
	v_cmp_gt_i32_e64 s[66:67], 2, v64
	v_cmp_gt_i32_e64 s[42:43], 34, v64
	v_cmp_gt_i32_e64 s[72:73], 3, v64
	v_mfma_f32_32x32x16_bf16 v[66:81], v[66:69], v[122:125], 0
	v_cmp_gt_i32_e64 s[44:45], 35, v64
	v_cmp_gt_i32_e64 s[76:77], 8, v64
	v_cmp_gt_i32_e64 s[46:47], 40, v64
	v_cmp_gt_i32_e64 s[80:81], 9, v64
	v_cmp_gt_i32_e64 s[48:49], 41, v64
	v_cmp_gt_i32_e64 s[82:83], 10, v64
	v_cmp_gt_i32_e64 s[50:51], 42, v64
	v_mfma_f32_32x32x16_bf16 v[82:97], v[130:133], v[114:117], v[82:97]
	v_cndmask_b32_e64 v130, 0, 1, s[4:5]
	v_cmp_ne_u32_e64 s[0:1], 1, v130
	v_cmp_gt_i32_e64 s[84:85], 11, v64
	v_cmp_gt_i32_e64 s[52:53], 43, v64
	v_cmp_gt_i32_e64 s[86:87], 16, v64
	v_cmp_gt_i32_e64 s[54:55], 48, v64
	v_cmp_gt_i32_e64 s[90:91], 17, v64
	v_mfma_f32_32x32x16_bf16 v[66:81], v[134:137], v[114:117], v[66:81]
	v_cmp_gt_i32_e64 s[60:61], 49, v64
	v_cmp_gt_i32_e64 s[92:93], 18, v64
	v_cmp_gt_i32_e64 s[64:65], 50, v64
	v_cmp_gt_i32_e64 s[94:95], 19, v64
	v_cmp_gt_i32_e64 s[68:69], 51, v64
	v_cmp_gt_i32_e64 s[96:97], 24, v64
	v_cmp_gt_i32_e64 s[70:71], 56, v64
	v_cmp_gt_i32_e64 s[6:7], 25, v64
	v_cmp_gt_i32_e64 s[74:75], 57, v64
	v_cmp_gt_i32_e64 s[4:5], 26, v64
	v_cmp_gt_i32_e64 s[78:79], 58, v64
	v_cmp_gt_i32_e64 s[88:89], 27, v64
	v_cmp_gt_i32_e64 s[56:57], 59, v64
	s_cbranch_vccnz .LBB0_1024
	s_and_b64 vcc, s[88:89], s[4:5]
	v_cndmask_b32_e32 v96, v96, v225, vcc
	s_and_b64 vcc, vcc, s[6:7]
	v_cndmask_b32_e32 v95, v95, v225, vcc
	s_and_b64 vcc, vcc, s[96:97]
	v_cndmask_b32_e32 v94, v94, v225, vcc
	s_and_b64 vcc, vcc, s[94:95]
	v_cndmask_b32_e32 v93, v93, v225, vcc
	s_and_b64 vcc, vcc, s[92:93]
	v_cndmask_b32_e32 v92, v92, v225, vcc
	s_and_b64 vcc, vcc, s[90:91]
	v_cndmask_b32_e32 v91, v91, v225, vcc
	s_and_b64 vcc, vcc, s[86:87]
	v_cndmask_b32_e32 v90, v90, v225, vcc
	s_and_b64 vcc, vcc, s[84:85]
	v_cndmask_b32_e32 v89, v89, v225, vcc
	s_and_b64 vcc, vcc, s[82:83]
	v_cndmask_b32_e32 v88, v88, v225, vcc
	s_and_b64 vcc, vcc, s[80:81]
	v_cndmask_b32_e32 v87, v87, v225, vcc
	s_and_b64 vcc, vcc, s[76:77]
	v_cndmask_b32_e32 v86, v86, v225, vcc
	s_and_b64 vcc, vcc, s[72:73]
	v_cndmask_b32_e32 v85, v85, v225, vcc
	s_and_b64 vcc, vcc, s[66:67]
	v_cndmask_b32_e32 v84, v84, v225, vcc
	s_and_b64 vcc, vcc, s[62:63]
	v_cndmask_b32_e32 v83, v83, v225, vcc
	s_and_b64 vcc, vcc, s[58:59]
	v_cndmask_b32_e32 v82, v82, v225, vcc
	s_and_b64 vcc, s[56:57], s[78:79]
	v_cndmask_b32_e32 v80, v80, v225, vcc
	s_and_b64 vcc, vcc, s[74:75]
	v_cndmask_b32_e32 v79, v79, v225, vcc
	s_and_b64 vcc, vcc, s[70:71]
	v_cndmask_b32_e32 v78, v78, v225, vcc
	s_and_b64 vcc, vcc, s[68:69]
	v_cndmask_b32_e32 v77, v77, v225, vcc
	s_and_b64 vcc, vcc, s[64:65]
	v_cndmask_b32_e32 v76, v76, v225, vcc
	s_and_b64 vcc, vcc, s[60:61]
	v_cndmask_b32_e32 v75, v75, v225, vcc
	s_and_b64 vcc, vcc, s[54:55]
	v_cndmask_b32_e32 v74, v74, v225, vcc
	s_and_b64 vcc, vcc, s[52:53]
	v_cndmask_b32_e32 v73, v73, v225, vcc
	s_and_b64 vcc, vcc, s[50:51]
	v_cndmask_b32_e32 v72, v72, v225, vcc
	s_and_b64 vcc, vcc, s[48:49]
	v_cndmask_b32_e32 v71, v71, v225, vcc
	s_and_b64 vcc, vcc, s[46:47]
	v_cndmask_b32_e32 v70, v70, v225, vcc
	s_and_b64 vcc, vcc, s[44:45]
	v_cndmask_b32_e32 v69, v69, v225, vcc
	s_and_b64 vcc, vcc, s[42:43]
	v_cndmask_b32_e32 v68, v68, v225, vcc
	s_and_b64 vcc, vcc, s[38:39]
	v_cndmask_b32_e32 v67, v67, v225, vcc
	s_and_b64 vcc, vcc, s[36:37]
	v_cndmask_b32_e64 v97, v97, v225, s[88:89]
	v_cndmask_b32_e32 v66, v66, v225, vcc
	v_cndmask_b32_e64 v81, v81, v225, s[56:57]
